# R5 QK->SV seam: dropped the no-op second vmcnt(0) after the s_barrier (waitcnt placement)
# speedup vs baseline: 1.0025x; 1.0025x over previous
; template <class Epi, class Sched>
; __device__ __forceinline__ void gemm_phase(LAS unsigned char* lds, const Sched& S, const Epi& E) {
;     ...
;     int sR, sRb, sC2;
;     { int R, C; stage_rc(tid * 16, R, C); sR = R; sRb = (R & ~31) + perm32(R & 31); sC2 = C * 2; }
;     const size_t kstep = (size_t)(BK * 2);
;     const unsigned ldsbase = (unsigned)(size_t)lds + (unsigned)wid * 1024u;
;     const int aoff = lds_byte(wr * 64 + fr, fq * 8), boff = lds_byte(wc * 32 + fr, fq * 8);
;     ...
;     int ui = 0;
;     const char* cA; const char* cB; unsigned hA, hB; int nt; unsigned voffA, voffB;
;     { Unit u0; if (!S.next(0, u0)) return;
;       cA = u0.A; cB = u0.B; hA = (unsigned)HALF * u0.lda2; hB = (unsigned)HALF * u0.ldb2; nt = u0.nt;
;       voffA = (unsigned)(sR * u0.lda2 + sC2); voffB = (unsigned)(sRb * u0.ldb2 + sC2); }
;     f32x4 acc[2][2][4][2];
; #pragma unroll
;     for (int a = 0; a < 2; ++a)
; #pragma unroll
;         for (int b = 0; b < 2; ++b)
; #pragma unroll
;             for (int m = 0; m < 4; ++m)
; #pragma unroll
;                 for (int n = 0; n < 2; ++n) acc[a][b][m][n] = (f32x4){0.f, 0.f, 0.f, 0.f};
;     bf16x8 At[4][2], B0[2][2], B1[2][2];
;     PG8_STAGE(PG8_SB(0, 0), cB, voffB, hB / 2); PG8_STAGE(PG8_SB(0, 1), cB + hB, voffB, hB / 2); PG8_STAGE(PG8_SA(0, 0), cA, voffA, hA / 2); PG8_STAGE(PG8_SA(0, 1), cA + hA, voffA, hA / 2);
; __global__ void __launch_bounds__(512, 2) fwd_megakernel(Params Parg) {
;     ...
;             __builtin_amdgcn_fence(__ATOMIC_ACQUIRE, "agent");
;             { PHASE_BEGIN
;               bf16_t* pscr = (bf16_t*)(ws + WS_PSCR + (size_t)(bid >> 1) * (256 * D * 2) + (size_t)(bid & 1) * (CH * 2));
;               const int ib = item & 1, h = (item >> 1) & 3, n = item >> 3;
;               SVSched S{(const char*)(ws + WS_KTQK) + ((size_t)(n * CH + ib * 256) * D + h * 256) * 2, (const char*)(ws + WS_SB) + ((size_t)((h * NCH + n) * 512) * 512) * 2,
;                         (const char*)(ws + WS_VT) + ((size_t)((h * NCH + n) * 512) * 512) * 2, (const char*)pscr, item};
;               EpiSV E; E.o = (bf16_t*)pp->out + (size_t)b * L * 2048; E.dec = WSP(float, WS_DEC); gemm_phase(lds, S, E); }
.LBB0_836:
	v_readlane_b32 s0, v254, 62
	v_readlane_b32 s1, v254, 63
	s_mov_b64 s[4:5], s[0:1]
	s_waitcnt vmcnt(0)
	s_barrier
	buffer_inv sc0
	s_load_dwordx4 s[8:11], s[4:5], 0xc8
	s_ashr_i32 s6, s73, 3
	s_lshl_b32 s7, s6, 9
	s_or_b32 s4, s7, s51
	s_ashr_i32 s5, s4, 31
	s_lshl_b32 s12, s72, 9
	s_lshl_b64 s[4:5], s[4:5], 11
	v_mov_b32_e32 v0, v176
	s_waitcnt lgkmcnt(0)
	s_add_u32 s4, s10, s4
	s_addc_u32 s5, s11, s5
	s_add_u32 s34, s4, s12
	v_mov_b32_e32 v0, v176
	s_addc_u32 s35, s5, 0
	s_add_u32 s26, s34, 0x8900000
	v_bfe_i32 v3, v0, 27, 1
	v_lshlrev_b32_e32 v1, 4, v0
	v_lshrrev_b32_e32 v3, 22, v3
	s_addc_u32 s27, s35, 0
	s_lshl_b32 s4, s72, 14
	v_add_u32_e32 v3, v1, v3
	s_add_i32 s4, s4, s7
	v_and_b32_e32 v3, 0xfffffc00, v3
	s_ashr_i32 s5, s4, 31
	v_sub_u32_e32 v1, v1, v3
	s_lshl_b64 s[16:17], s[4:5], 10
	v_ashrrev_i32_e32 v2, 31, v0
	v_lshrrev_b32_e32 v3, 4, v1
	s_add_u32 s7, s10, s16
	v_lshrrev_b32_e32 v2, 26, v2
	v_bitop3_b32 v1, v3, v1, 32 bitop3:0x6c
	s_addc_u32 s24, s11, s17
	v_add_u32_e32 v2, v0, v2
	v_ashrrev_i32_e32 v4, 31, v1
	s_add_u32 s38, s7, 0x10900000
	v_readfirstlane_b32 s22, v0
	v_ashrrev_i32_e32 v2, 6, v2
	v_lshrrev_b32_e32 v4, 26, v4
	s_addc_u32 s39, s24, 0
	s_ashr_i32 s48, s22, 6
	v_lshlrev_b32_e32 v3, 3, v2
	v_add_u32_e32 v4, v1, v4
	v_and_b32_e32 v3, -16, v3
	v_ashrrev_i32_e32 v5, 6, v4
	v_and_b32_e32 v4, 0xc0, v4
	s_lshl_b32 s4, s48, 10
	v_add_u32_e32 v3, v5, v3
	v_sub_u32_e32 v1, v1, v4
	v_and_b32_e32 v5, 3, v5
	s_mov_b32 s5, 0x3fffe0
	s_add_i32 s4, s4, 0
	s_ashr_i32 s23, s22, 8
	v_lshlrev_b32_e32 v2, 5, v2
	v_ashrrev_i16_sdwa v1, v157, sext(v1) dst_sel:DWORD dst_unused:UNUSED_PAD src0_sel:DWORD src1_sel:BYTE_0
	v_lshlrev_b32_e32 v4, 1, v3
	v_lshrrev_b32_e32 v6, 2, v3
	v_and_or_b32 v5, v3, s5, v5
	s_add_i32 s5, s4, 0x10000
	v_bfe_i32 v1, v1, 0, 16
	v_and_b32_e32 v4, 24, v4
	v_and_b32_e32 v6, 4, v6
	v_and_b32_e32 v2, 32, v2
	s_add_u32 s14, s7, 0x10910000
	v_or3_b32 v4, v5, v6, v4
	v_add_lshl_u32 v1, v2, v1, 1
	s_addc_u32 s15, s24, 0
	s_add_i32 s12, s4, 0x12000
	v_lshl_add_u32 v128, v4, 10, v1
	s_mov_b32 m0, s5
	s_nop 0
	global_load_lds_dwordx4 v128, s[38:39]
	s_mov_b32 m0, s12
	s_add_u32 s30, s7, 0x10920000
	global_load_lds_dwordx4 v128, s[14:15]
	s_addc_u32 s31, s24, 0
	s_add_i32 s14, s4, 0x14000
	s_mov_b32 m0, s14
	s_nop 0
	global_load_lds_dwordx4 v128, s[30:31]
	s_add_u32 s30, s7, 0x10930000
	s_addc_u32 s31, s24, 0
	s_add_i32 s15, s4, 0x16000
	s_mov_b32 m0, s15
	s_nop 0
	global_load_lds_dwordx4 v128, s[30:31]
	s_add_u32 s30, s34, 0x8920000
	v_lshl_add_u32 v172, v3, 11, v1
	s_mov_b32 m0, s4
	s_nop 0
	global_load_lds_dwordx4 v172, s[26:27]
	s_addc_u32 s31, s35, 0
	s_add_i32 s24, s4, 0x2000
	s_mov_b32 m0, s24
	s_nop 0
	global_load_lds_dwordx4 v172, s[30:31]
	s_add_u32 s30, s34, 0x8940000
	s_addc_u32 s31, s35, 0
	s_add_i32 s33, s4, 0x4000
	s_mov_b32 m0, s33
	s_nop 0
	global_load_lds_dwordx4 v172, s[30:31]
	s_add_u32 s30, s34, 0x8960000
	s_addc_u32 s31, s35, 0
	s_add_i32 s34, s4, 0x6000
	s_mov_b32 m0, s34
	s_nop 0
	global_load_lds_dwordx4 v172, s[30:31]
	s_cmp_eq_u32 s23, 1
	s_cselect_b64 s[40:41], -1, 0
	s_cmp_lg_u32 s23, 1
	s_cbranch_scc1 .LBB0_838
	s_barrier
